# GEMM K-loops (up-proj, in-proj): LDS-DMA loads use SGPR base + 32-bit VGPR offset instead of per-lane 64-bit VALU address adds
# baseline (speedup 1.0000x reference)
; #define PG8_STAGE(bufoff, gbase, voff) do { _Pragma("unroll") for (int _i = 0; _i < 2; ++_i) \
;         __builtin_amdgcn_global_load_lds((const unsigned*)((const char*)(gbase) + (voff)[_i]), (PG8_LAS unsigned*)(lds + (bufoff) + ldsw + _i * 8192), 16, 0, 0); } while (0)
; #define PG8_LDA(dst, b, h) do { _Pragma("unroll") for (int m = 0; m < 4; ++m) _Pragma("unroll") for (int k = 0; k < 2; ++k) dst[m][k] = *(const PG8_LAS bf16x8*)(lds + PG8_SA(b, h) + aoff + m * 2048 + k * 1024); } while (0)
; #define PG8_LDB(dst, b, h) do { _Pragma("unroll") for (int n = 0; n < 2; ++n) _Pragma("unroll") for (int k = 0; k < 2; ++k) dst[n][k] = *(const PG8_LAS bf16x8*)(lds + PG8_SB(b, h) + boff + n * 2048 + k * 1024); } while (0)
; #define PG8_MMA(ai, bj, At, Bt) do { __builtin_amdgcn_s_setprio(1); _Pragma("unroll") for (int m = 0; m < 4; ++m) _Pragma("unroll") for (int n = 0; n < 2; ++n) _Pragma("unroll") for (int k = 0; k < 2; ++k) \
;         acc[ai][bj][m][n] = __builtin_amdgcn_mfma_f32_16x16x32_bf16(Bt[n][k], At[m][k], acc[ai][bj][m][n], 0, 0, 0); __builtin_amdgcn_s_setprio(0); } while (0)
; #define PG8_WAIT_V(n) asm volatile("s_waitcnt vmcnt(" #n ")" ::: "memory")
; #define PG8_WAIT_L(n) asm volatile("s_waitcnt lgkmcnt(" #n ")" ::: "memory")
; #define PG8_BAR __builtin_amdgcn_s_barrier()
; #define PG8_SCHED __builtin_amdgcn_sched_barrier(0)
; template <class Epi, class Sched, bool ALIGN_EPI = false, bool SP2 = false>
; __device__ __forceinline__ void gemm_phase(PG8_LAS unsigned char* lds, const Gemm g, const Sched& S, const Epi& E, int tid_in) {
;     ...
;             PG8_LDB(B0, 0, 0); PG8_LDB(B1, 0, 1); PG8_SCHED; PG8_LDA(At, 0, 0); PG8_STAGE(PG8_SA(1, 1), a1 + hstep, voffA);
;             PG8_WAIT_V(8); PG8_WAIT_L(0); PG8_BAR; PG8_MMA(0, 0, At, B0); PG8_MMA(0, 1, At, B1); PG8_BAR; PG8_SCHED;
;             PG8_LDA(At, 0, 1); PG8_STAGE(PG8_SB(0, 0), b2, voffB); PG8_STAGE(PG8_SB(0, 1), b2 + hstep, voffB); PG8_STAGE(PG8_SA(0, 0), a2, voffA);
;             PG8_WAIT_V(8); PG8_WAIT_L(0); PG8_BAR; PG8_MMA(1, 0, At, B0); PG8_MMA(1, 1, At, B1); PG8_BAR; PG8_SCHED;
.LBB0_219:
	s_add_u32 s0, s24, 0xfffc0080
	s_addc_u32 s1, s25, -1
	s_add_i32 s2, 0, 0x10000
	s_cmp_eq_u32 s55, 12
	s_cselect_b32 s29, s7, s1
	s_cselect_b32 s28, s9, s0
	s_cselect_b32 s27, s17, s54
	s_cselect_b32 s26, s19, s53
	s_add_i32 s3, 0, 0x14000
	v_add_u32_e32 v140, s2, v168
	v_add_u32_e32 v174, s3, v168
	ds_read_b128 v[128:131], v140
	ds_read_b128 v[132:135], v140 offset:1024
	ds_read_b128 v[136:139], v140 offset:2048
	ds_read_b128 v[140:143], v140 offset:3072
	ds_read_b128 v[158:161], v174
	ds_read_b128 v[162:165], v174 offset:1024
	ds_read_b128 v[170:173], v174 offset:2048
	ds_read_b128 v[174:177], v174 offset:3072
	s_add_i32 m0, s41, 0xc000
	ds_read_b128 v[178:181], v169
	ds_read_b128 v[182:185], v169 offset:1024
	ds_read_b128 v[186:189], v169 offset:2048
	ds_read_b128 v[190:193], v169 offset:3072
	ds_read_b128 v[194:197], v169 offset:4096
	ds_read_b128 v[198:201], v169 offset:5120
	ds_read_b128 v[202:205], v169 offset:6144
	ds_read_b128 v[206:209], v169 offset:7168
	global_load_lds_dwordx4 v154, s[24:25]
	s_add_i32 m0, s41, 0xe000
	s_nop 0
	global_load_lds_dwordx4 v156, s[24:25]
	s_waitcnt vmcnt(8)
	s_waitcnt lgkmcnt(0)
	s_barrier
	s_setprio 1
	s_waitcnt lgkmcnt(0)
	v_mfma_f32_16x16x32_bf16 v[124:127], v[128:131], v[178:181], v[124:127]
	v_mfma_f32_16x16x32_bf16 v[120:123], v[136:139], v[178:181], v[120:123]
	v_mfma_f32_16x16x32_bf16 v[108:111], v[128:131], v[186:189], v[108:111]
	v_mfma_f32_16x16x32_bf16 v[104:107], v[136:139], v[186:189], v[104:107]
	v_mfma_f32_16x16x32_bf16 v[92:95], v[128:131], v[194:197], v[92:95]
	v_mfma_f32_16x16x32_bf16 v[88:91], v[136:139], v[194:197], v[88:91]
	v_mfma_f32_16x16x32_bf16 v[76:79], v[128:131], v[202:205], v[76:79]
	v_mfma_f32_16x16x32_bf16 v[72:75], v[136:139], v[202:205], v[72:75]
	v_mfma_f32_16x16x32_bf16 v[124:127], v[132:135], v[182:185], v[124:127]
	v_mfma_f32_16x16x32_bf16 v[120:123], v[140:143], v[182:185], v[120:123]
	v_mfma_f32_16x16x32_bf16 v[108:111], v[132:135], v[190:193], v[108:111]
	v_mfma_f32_16x16x32_bf16 v[104:107], v[140:143], v[190:193], v[104:107]
	v_mfma_f32_16x16x32_bf16 v[92:95], v[132:135], v[198:201], v[92:95]
	v_mfma_f32_16x16x32_bf16 v[88:91], v[140:143], v[198:201], v[88:91]
	v_mfma_f32_16x16x32_bf16 v[76:79], v[132:135], v[206:209], v[76:79]
	v_mfma_f32_16x16x32_bf16 v[72:75], v[140:143], v[206:209], v[72:75]
	s_setprio 0
	s_setprio 1
	v_mfma_f32_16x16x32_bf16 v[116:119], v[158:161], v[178:181], v[116:119]
	v_mfma_f32_16x16x32_bf16 v[112:115], v[170:173], v[178:181], v[112:115]
	v_mfma_f32_16x16x32_bf16 v[100:103], v[158:161], v[186:189], v[100:103]
	v_mfma_f32_16x16x32_bf16 v[96:99], v[170:173], v[186:189], v[96:99]
	v_mfma_f32_16x16x32_bf16 v[84:87], v[158:161], v[194:197], v[84:87]
	v_mfma_f32_16x16x32_bf16 v[80:83], v[170:173], v[194:197], v[80:83]
	v_mfma_f32_16x16x32_bf16 v[68:71], v[158:161], v[202:205], v[68:71]
	v_mfma_f32_16x16x32_bf16 v[64:67], v[170:173], v[202:205], v[64:67]
	v_mfma_f32_16x16x32_bf16 v[116:119], v[162:165], v[182:185], v[116:119]
	v_mfma_f32_16x16x32_bf16 v[112:115], v[174:177], v[182:185], v[112:115]
	v_mfma_f32_16x16x32_bf16 v[100:103], v[162:165], v[190:193], v[100:103]
	v_mfma_f32_16x16x32_bf16 v[96:99], v[174:177], v[190:193], v[96:99]
	v_mfma_f32_16x16x32_bf16 v[84:87], v[162:165], v[198:201], v[84:87]
	v_mfma_f32_16x16x32_bf16 v[80:83], v[174:177], v[198:201], v[80:83]
	v_mfma_f32_16x16x32_bf16 v[68:71], v[162:165], v[206:209], v[68:71]
	v_mfma_f32_16x16x32_bf16 v[64:67], v[174:177], v[206:209], v[64:67]
	s_setprio 0
	s_barrier
	s_add_i32 s0, s2, s40
	s_mov_b32 m0, s0
	ds_read_b128 v[178:181], v169 offset:16384
	ds_read_b128 v[182:185], v169 offset:17408
	ds_read_b128 v[186:189], v169 offset:18432
	ds_read_b128 v[190:193], v169 offset:19456
	ds_read_b128 v[194:197], v169 offset:20480
	ds_read_b128 v[198:201], v169 offset:21504
	ds_read_b128 v[202:205], v169 offset:22528
	ds_read_b128 v[206:209], v169 offset:23552
	global_load_lds_dwordx4 v144, s[26:27]
	s_add_i32 m0, s0, 0x2000
	s_add_u32 s0, s26, 0x40000
	s_addc_u32 s1, s27, 0
	s_add_i32 s2, s3, s40
	global_load_lds_dwordx4 v152, s[26:27]
	s_mov_b32 m0, s2
	s_nop 0
	global_load_lds_dwordx4 v144, s[0:1]
	s_add_i32 m0, s2, 0x2000
	s_nop 0
	global_load_lds_dwordx4 v152, s[0:1]
	s_mov_b32 m0, s41
	s_nop 0
	global_load_lds_dwordx4 v148, s[28:29]
	s_mov_b32 m0, s42
	s_nop 0
	global_load_lds_dwordx4 v150, s[28:29]
	s_waitcnt vmcnt(8)
	s_waitcnt lgkmcnt(0)
	s_barrier
	s_setprio 1
	s_waitcnt lgkmcnt(0)
	v_mfma_f32_16x16x32_bf16 v[60:63], v[128:131], v[178:181], v[60:63]
	v_mfma_f32_16x16x32_bf16 v[56:59], v[136:139], v[178:181], v[56:59]
	v_mfma_f32_16x16x32_bf16 v[44:47], v[128:131], v[186:189], v[44:47]
	v_mfma_f32_16x16x32_bf16 v[40:43], v[136:139], v[186:189], v[40:43]
	v_mfma_f32_16x16x32_bf16 v[28:31], v[128:131], v[194:197], v[28:31]
	v_mfma_f32_16x16x32_bf16 v[24:27], v[136:139], v[194:197], v[24:27]
	v_mfma_f32_16x16x32_bf16 v[12:15], v[128:131], v[202:205], v[12:15]
	v_mfma_f32_16x16x32_bf16 v[8:11], v[136:139], v[202:205], v[8:11]
	v_mfma_f32_16x16x32_bf16 v[60:63], v[132:135], v[182:185], v[60:63]
	v_mfma_f32_16x16x32_bf16 v[56:59], v[140:143], v[182:185], v[56:59]
	v_mfma_f32_16x16x32_bf16 v[44:47], v[132:135], v[190:193], v[44:47]
	v_mfma_f32_16x16x32_bf16 v[40:43], v[140:143], v[190:193], v[40:43]
	v_mfma_f32_16x16x32_bf16 v[28:31], v[132:135], v[198:201], v[28:31]
	v_mfma_f32_16x16x32_bf16 v[24:27], v[140:143], v[198:201], v[24:27]
	v_mfma_f32_16x16x32_bf16 v[12:15], v[132:135], v[206:209], v[12:15]
	v_mfma_f32_16x16x32_bf16 v[8:11], v[140:143], v[206:209], v[8:11]
	s_setprio 0
	s_setprio 1
	v_mfma_f32_16x16x32_bf16 v[52:55], v[158:161], v[178:181], v[52:55]
	v_mfma_f32_16x16x32_bf16 v[48:51], v[170:173], v[178:181], v[48:51]
	v_mfma_f32_16x16x32_bf16 v[36:39], v[158:161], v[186:189], v[36:39]
	v_mfma_f32_16x16x32_bf16 v[32:35], v[170:173], v[186:189], v[32:35]
	v_mfma_f32_16x16x32_bf16 v[20:23], v[158:161], v[194:197], v[20:23]
	v_mfma_f32_16x16x32_bf16 v[16:19], v[170:173], v[194:197], v[16:19]
	v_mfma_f32_16x16x32_bf16 v[4:7], v[158:161], v[202:205], v[4:7]
	v_mfma_f32_16x16x32_bf16 v[0:3], v[170:173], v[202:205], v[0:3]
	v_mfma_f32_16x16x32_bf16 v[52:55], v[162:165], v[182:185], v[52:55]
	v_mfma_f32_16x16x32_bf16 v[48:51], v[174:177], v[182:185], v[48:51]
	v_mfma_f32_16x16x32_bf16 v[36:39], v[162:165], v[190:193], v[36:39]
	v_mfma_f32_16x16x32_bf16 v[32:35], v[174:177], v[190:193], v[32:35]
	v_mfma_f32_16x16x32_bf16 v[20:23], v[162:165], v[198:201], v[20:23]
	v_mfma_f32_16x16x32_bf16 v[16:19], v[174:177], v[198:201], v[16:19]
	v_mfma_f32_16x16x32_bf16 v[4:7], v[162:165], v[206:209], v[4:7]
	v_mfma_f32_16x16x32_bf16 v[0:3], v[174:177], v[206:209], v[0:3]
	s_setprio 0
	s_barrier
; #define PG8_STAGE(bufoff, gbase, voff) do { _Pragma("unroll") for (int _i = 0; _i < 2; ++_i) \
;         __builtin_amdgcn_global_load_lds((const unsigned*)((const char*)(gbase) + (voff)[_i]), (PG8_LAS unsigned*)(lds + (bufoff) + ldsw + _i * 8192), 16, 0, 0); } while (0)
; #define PG8_LDA(dst, b, h) do { _Pragma("unroll") for (int m = 0; m < 4; ++m) _Pragma("unroll") for (int k = 0; k < 2; ++k) dst[m][k] = *(const PG8_LAS bf16x8*)(lds + PG8_SA(b, h) + aoff + m * 2048 + k * 1024); } while (0)
; #define PG8_LDB(dst, b, h) do { _Pragma("unroll") for (int n = 0; n < 2; ++n) _Pragma("unroll") for (int k = 0; k < 2; ++k) dst[n][k] = *(const PG8_LAS bf16x8*)(lds + PG8_SB(b, h) + boff + n * 2048 + k * 1024); } while (0)
; #define PG8_MMA(ai, bj, At, Bt) do { __builtin_amdgcn_s_setprio(1); _Pragma("unroll") for (int m = 0; m < 4; ++m) _Pragma("unroll") for (int n = 0; n < 2; ++n) _Pragma("unroll") for (int k = 0; k < 2; ++k) \
;         acc[ai][bj][m][n] = __builtin_amdgcn_mfma_f32_16x16x32_bf16(Bt[n][k], At[m][k], acc[ai][bj][m][n], 0, 0, 0); __builtin_amdgcn_s_setprio(0); } while (0)
; #define PG8_WAIT_V(n) asm volatile("s_waitcnt vmcnt(" #n ")" ::: "memory")
; #define PG8_WAIT_L(n) asm volatile("s_waitcnt lgkmcnt(" #n ")" ::: "memory")
; #define PG8_BAR __builtin_amdgcn_s_barrier()
; template <class Epi, class Sched, bool ALIGN_EPI = false, bool SP2 = false>
; __device__ __forceinline__ void gemm_phase(PG8_LAS unsigned char* lds, const Gemm g, const Sched& S, const Epi& E, int tid_in) {
;     ...
;         for (int t = 0; t < nt; t += 2) {
;             const bool last = (t == nt - 2);
;             const char* a1 = cA + (size_t)(t + 1) * kstep;
;             const char* a2 = last ? nA : cA + (size_t)(t + 2) * kstep; const char* b2 = last ? nB : cB + (size_t)(t + 2) * kstep;
;             const char* a3 = a2 + kstep; const char* b3 = b2 + kstep;
;     ...
;             PG8_LDB(B0, 1, 0); PG8_LDB(B1, 1, 1); PG8_SCHED; PG8_LDA(At, 1, 0); PG8_STAGE(PG8_SA(0, 1), a2 + hstep, voffA);
;             PG8_WAIT_V(8); PG8_WAIT_L(0); PG8_BAR; PG8_MMA(0, 0, At, B0); PG8_MMA(0, 1, At, B1); PG8_BAR; PG8_SCHED;
;             PG8_LDA(At, 1, 1); PG8_STAGE(PG8_SB(1, 0), b3, voffB); PG8_STAGE(PG8_SB(1, 1), b3 + hstep, voffB); PG8_STAGE(PG8_SA(1, 0), a3, voffA);
;             PG8_WAIT_V(8); PG8_WAIT_L(0); PG8_BAR; PG8_MMA(1, 0, At, B0); PG8_MMA(1, 1, At, B1); PG8_BAR; PG8_SCHED;
	s_add_i32 s2, 0, 0x18000
	s_add_i32 s3, 0, 0x1c000
	v_add_u32_e32 v140, s2, v168
	v_add_u32_e32 v174, s3, v168
	ds_read_b128 v[128:131], v140
	ds_read_b128 v[132:135], v140 offset:1024
	ds_read_b128 v[136:139], v140 offset:2048
	ds_read_b128 v[140:143], v140 offset:3072
	ds_read_b128 v[158:161], v174
	ds_read_b128 v[162:165], v174 offset:1024
	ds_read_b128 v[170:173], v174 offset:2048
	ds_read_b128 v[174:177], v174 offset:3072
	s_add_u32 s0, s28, 0x40000
	s_addc_u32 s1, s29, 0
	s_mov_b32 m0, s43
	ds_read_b128 v[178:181], v169 offset:32768
	ds_read_b128 v[182:185], v169 offset:33792
	ds_read_b128 v[186:189], v169 offset:34816
	ds_read_b128 v[190:193], v169 offset:35840
	ds_read_b128 v[194:197], v169 offset:36864
	ds_read_b128 v[198:201], v169 offset:37888
	ds_read_b128 v[202:205], v169 offset:38912
	ds_read_b128 v[206:209], v169 offset:39936
	global_load_lds_dwordx4 v148, s[0:1]
	s_mov_b32 m0, s44
	s_nop 0
	global_load_lds_dwordx4 v150, s[0:1]
	s_waitcnt vmcnt(8)
	s_waitcnt lgkmcnt(0)
	s_barrier
	s_setprio 1
	s_waitcnt lgkmcnt(0)
	v_mfma_f32_16x16x32_bf16 v[124:127], v[128:131], v[178:181], v[124:127]
	v_mfma_f32_16x16x32_bf16 v[120:123], v[136:139], v[178:181], v[120:123]
	v_mfma_f32_16x16x32_bf16 v[108:111], v[128:131], v[186:189], v[108:111]
	v_mfma_f32_16x16x32_bf16 v[104:107], v[136:139], v[186:189], v[104:107]
	v_mfma_f32_16x16x32_bf16 v[92:95], v[128:131], v[194:197], v[92:95]
	v_mfma_f32_16x16x32_bf16 v[88:91], v[136:139], v[194:197], v[88:91]
	v_mfma_f32_16x16x32_bf16 v[76:79], v[128:131], v[202:205], v[76:79]
	v_mfma_f32_16x16x32_bf16 v[72:75], v[136:139], v[202:205], v[72:75]
	v_mfma_f32_16x16x32_bf16 v[124:127], v[132:135], v[182:185], v[124:127]
	v_mfma_f32_16x16x32_bf16 v[120:123], v[140:143], v[182:185], v[120:123]
	v_mfma_f32_16x16x32_bf16 v[108:111], v[132:135], v[190:193], v[108:111]
	v_mfma_f32_16x16x32_bf16 v[104:107], v[140:143], v[190:193], v[104:107]
	v_mfma_f32_16x16x32_bf16 v[92:95], v[132:135], v[198:201], v[92:95]
	v_mfma_f32_16x16x32_bf16 v[88:91], v[140:143], v[198:201], v[88:91]
	v_mfma_f32_16x16x32_bf16 v[76:79], v[132:135], v[206:209], v[76:79]
	v_mfma_f32_16x16x32_bf16 v[72:75], v[140:143], v[206:209], v[72:75]
	s_setprio 0
	s_setprio 1
	v_mfma_f32_16x16x32_bf16 v[116:119], v[158:161], v[178:181], v[116:119]
	v_mfma_f32_16x16x32_bf16 v[112:115], v[170:173], v[178:181], v[112:115]
	v_mfma_f32_16x16x32_bf16 v[100:103], v[158:161], v[186:189], v[100:103]
	v_mfma_f32_16x16x32_bf16 v[96:99], v[170:173], v[186:189], v[96:99]
	v_mfma_f32_16x16x32_bf16 v[84:87], v[158:161], v[194:197], v[84:87]
	v_mfma_f32_16x16x32_bf16 v[80:83], v[170:173], v[194:197], v[80:83]
	v_mfma_f32_16x16x32_bf16 v[68:71], v[158:161], v[202:205], v[68:71]
	v_mfma_f32_16x16x32_bf16 v[64:67], v[170:173], v[202:205], v[64:67]
	v_mfma_f32_16x16x32_bf16 v[116:119], v[162:165], v[182:185], v[116:119]
	v_mfma_f32_16x16x32_bf16 v[112:115], v[174:177], v[182:185], v[112:115]
	v_mfma_f32_16x16x32_bf16 v[100:103], v[162:165], v[190:193], v[100:103]
	v_mfma_f32_16x16x32_bf16 v[96:99], v[174:177], v[190:193], v[96:99]
	v_mfma_f32_16x16x32_bf16 v[84:87], v[162:165], v[198:201], v[84:87]
	v_mfma_f32_16x16x32_bf16 v[80:83], v[174:177], v[198:201], v[80:83]
	v_mfma_f32_16x16x32_bf16 v[68:71], v[162:165], v[206:209], v[68:71]
	v_mfma_f32_16x16x32_bf16 v[64:67], v[174:177], v[206:209], v[64:67]
	s_setprio 0
	s_barrier
	s_add_i32 s0, s2, s40
	s_add_u32 s98, s26, 0x80
	s_addc_u32 s99, s27, 0
	s_mov_b32 m0, s0
	ds_read_b128 v[178:181], v169 offset:49152
	ds_read_b128 v[182:185], v169 offset:50176
	ds_read_b128 v[186:189], v169 offset:51200
	ds_read_b128 v[190:193], v169 offset:52224
	ds_read_b128 v[194:197], v169 offset:53248
	ds_read_b128 v[198:201], v169 offset:54272
	ds_read_b128 v[202:205], v169 offset:55296
	ds_read_b128 v[206:209], v169 offset:56320
	global_load_lds_dwordx4 v144, s[98:99]
	s_add_i32 m0, s0, 0x2000
	s_add_u32 s0, s26, 0x40080
	s_addc_u32 s1, s27, 0
	s_add_i32 s2, s3, s40
	global_load_lds_dwordx4 v152, s[98:99]
	s_mov_b32 m0, s2
	s_nop 0
	global_load_lds_dwordx4 v144, s[0:1]
	s_add_i32 m0, s2, 0x2000
	s_nop 0
	global_load_lds_dwordx4 v152, s[0:1]
	s_add_u32 s98, s28, 0x80
	s_addc_u32 s99, s29, 0
	s_mov_b32 m0, s50
	s_nop 0
	global_load_lds_dwordx4 v148, s[98:99]
	s_mov_b32 m0, s51
	s_nop 0
	global_load_lds_dwordx4 v150, s[98:99]
	s_waitcnt vmcnt(8)
	s_waitcnt lgkmcnt(0)
	s_barrier
	s_setprio 1
	s_waitcnt lgkmcnt(0)
	v_mfma_f32_16x16x32_bf16 v[60:63], v[128:131], v[178:181], v[60:63]
	v_mfma_f32_16x16x32_bf16 v[56:59], v[136:139], v[178:181], v[56:59]
	v_mfma_f32_16x16x32_bf16 v[44:47], v[128:131], v[186:189], v[44:47]
	v_mfma_f32_16x16x32_bf16 v[40:43], v[136:139], v[186:189], v[40:43]
	v_mfma_f32_16x16x32_bf16 v[28:31], v[128:131], v[194:197], v[28:31]
	v_mfma_f32_16x16x32_bf16 v[24:27], v[136:139], v[194:197], v[24:27]
	v_mfma_f32_16x16x32_bf16 v[12:15], v[128:131], v[202:205], v[12:15]
	v_mfma_f32_16x16x32_bf16 v[8:11], v[136:139], v[202:205], v[8:11]
	v_mfma_f32_16x16x32_bf16 v[60:63], v[132:135], v[182:185], v[60:63]
	v_mfma_f32_16x16x32_bf16 v[56:59], v[140:143], v[182:185], v[56:59]
	v_mfma_f32_16x16x32_bf16 v[44:47], v[132:135], v[190:193], v[44:47]
	v_mfma_f32_16x16x32_bf16 v[40:43], v[140:143], v[190:193], v[40:43]
	v_mfma_f32_16x16x32_bf16 v[28:31], v[132:135], v[198:201], v[28:31]
	v_mfma_f32_16x16x32_bf16 v[24:27], v[140:143], v[198:201], v[24:27]
	v_mfma_f32_16x16x32_bf16 v[12:15], v[132:135], v[206:209], v[12:15]
	v_mfma_f32_16x16x32_bf16 v[8:11], v[140:143], v[206:209], v[8:11]
	s_setprio 0
	s_setprio 1
	v_mfma_f32_16x16x32_bf16 v[52:55], v[158:161], v[178:181], v[52:55]
	v_mfma_f32_16x16x32_bf16 v[48:51], v[170:173], v[178:181], v[48:51]
	v_mfma_f32_16x16x32_bf16 v[36:39], v[158:161], v[186:189], v[36:39]
	v_mfma_f32_16x16x32_bf16 v[32:35], v[170:173], v[186:189], v[32:35]
	v_mfma_f32_16x16x32_bf16 v[20:23], v[158:161], v[194:197], v[20:23]
	v_mfma_f32_16x16x32_bf16 v[16:19], v[170:173], v[194:197], v[16:19]
	v_mfma_f32_16x16x32_bf16 v[4:7], v[158:161], v[202:205], v[4:7]
	v_mfma_f32_16x16x32_bf16 v[0:3], v[170:173], v[202:205], v[0:3]
	v_mfma_f32_16x16x32_bf16 v[52:55], v[162:165], v[182:185], v[52:55]
	v_mfma_f32_16x16x32_bf16 v[48:51], v[174:177], v[182:185], v[48:51]
	v_mfma_f32_16x16x32_bf16 v[36:39], v[162:165], v[190:193], v[36:39]
	v_mfma_f32_16x16x32_bf16 v[32:35], v[174:177], v[190:193], v[32:35]
	v_mfma_f32_16x16x32_bf16 v[20:23], v[162:165], v[198:201], v[20:23]
	v_mfma_f32_16x16x32_bf16 v[16:19], v[174:177], v[198:201], v[16:19]
	v_mfma_f32_16x16x32_bf16 v[4:7], v[162:165], v[206:209], v[4:7]
	v_mfma_f32_16x16x32_bf16 v[0:3], v[174:177], v[206:209], v[0:3]
	s_setprio 0
	s_barrier
	s_add_i32 s55, s55, 2
	s_add_u32 s24, s24, 0x100
	s_addc_u32 s25, s25, 0
	s_add_u32 s53, s53, 0x100
	s_addc_u32 s54, s54, 0
	s_cmp_gt_u32 s55, 13
	s_cbranch_scc0 .LBB0_219
	s_and_b64 vcc, exec, s[14:15]
	s_cbranch_vccz .LBB0_222
	s_barrier

; #define PG8_STAGE(bufoff, gbase, voff) do { _Pragma("unroll") for (int _i = 0; _i < 2; ++_i) \
;         __builtin_amdgcn_global_load_lds((const unsigned*)((const char*)(gbase) + (voff)[_i]), (PG8_LAS unsigned*)(lds + (bufoff) + ldsw + _i * 8192), 16, 0, 0); } while (0)
; #define PG8_LDA(dst, b, h) do { _Pragma("unroll") for (int m = 0; m < 4; ++m) _Pragma("unroll") for (int k = 0; k < 2; ++k) dst[m][k] = *(const PG8_LAS bf16x8*)(lds + PG8_SA(b, h) + aoff + m * 2048 + k * 1024); } while (0)
; #define PG8_LDB(dst, b, h) do { _Pragma("unroll") for (int n = 0; n < 2; ++n) _Pragma("unroll") for (int k = 0; k < 2; ++k) dst[n][k] = *(const PG8_LAS bf16x8*)(lds + PG8_SB(b, h) + boff + n * 2048 + k * 1024); } while (0)
; #define PG8_MMA(ai, bj, At, Bt) do { __builtin_amdgcn_s_setprio(1); _Pragma("unroll") for (int m = 0; m < 4; ++m) _Pragma("unroll") for (int n = 0; n < 2; ++n) _Pragma("unroll") for (int k = 0; k < 2; ++k) \
;         acc[ai][bj][m][n] = __builtin_amdgcn_mfma_f32_16x16x32_bf16(Bt[n][k], At[m][k], acc[ai][bj][m][n], 0, 0, 0); __builtin_amdgcn_s_setprio(0); } while (0)
; #define PG8_WAIT_V(n) asm volatile("s_waitcnt vmcnt(" #n ")" ::: "memory")
; #define PG8_WAIT_L(n) asm volatile("s_waitcnt lgkmcnt(" #n ")" ::: "memory")
; #define PG8_BAR __builtin_amdgcn_s_barrier()
; #define PG8_SCHED __builtin_amdgcn_sched_barrier(0)
; template <class Epi, class Sched, bool ALIGN_EPI = false, bool SP2 = false>
; __device__ __forceinline__ void gemm_phase(PG8_LAS unsigned char* lds, const Gemm g, const Sched& S, const Epi& E, int tid_in) {
;     ...
;             PG8_LDB(B0, 0, 0); PG8_LDB(B1, 0, 1); PG8_SCHED; PG8_LDA(At, 0, 0); PG8_STAGE(PG8_SA(1, 1), a1 + hstep, voffA);
;             PG8_WAIT_V(8); PG8_WAIT_L(0); PG8_BAR; PG8_MMA(0, 0, At, B0); PG8_MMA(0, 1, At, B1); PG8_BAR; PG8_SCHED;
;             PG8_LDA(At, 0, 1); PG8_STAGE(PG8_SB(0, 0), b2, voffB); PG8_STAGE(PG8_SB(0, 1), b2 + hstep, voffB); PG8_STAGE(PG8_SA(0, 0), a2, voffA);
;             PG8_WAIT_V(8); PG8_WAIT_L(0); PG8_BAR; PG8_MMA(1, 0, At, B0); PG8_MMA(1, 1, At, B1); PG8_BAR; PG8_SCHED;
.LBB0_351:
	s_add_u32 s2, s20, 0xfffc0080
	s_addc_u32 s3, s21, -1
	s_add_i32 s33, 0, 0x10000
	s_cmp_eq_u32 s49, 12
	s_cselect_b32 s25, s11, s3
	s_cselect_b32 s24, s44, s2
	s_cselect_b32 s23, s9, s48
	s_cselect_b32 s22, s45, s47
	s_add_i32 s34, 0, 0x14000
	v_add_u32_e32 v60, s33, v164
	v_add_u32_e32 v174, s34, v164
	ds_read_b128 v[48:51], v60
	ds_read_b128 v[52:55], v60 offset:1024
	ds_read_b128 v[56:59], v60 offset:2048
	ds_read_b128 v[60:63], v60 offset:3072
	ds_read_b128 v[158:161], v174
	ds_read_b128 v[166:169], v174 offset:1024
	ds_read_b128 v[170:173], v174 offset:2048
	ds_read_b128 v[174:177], v174 offset:3072
	s_add_i32 m0, s19, 0xc000
	ds_read_b128 v[178:181], v165
	ds_read_b128 v[182:185], v165 offset:1024
	ds_read_b128 v[186:189], v165 offset:2048
	ds_read_b128 v[190:193], v165 offset:3072
	ds_read_b128 v[194:197], v165 offset:4096
	ds_read_b128 v[198:201], v165 offset:5120
	ds_read_b128 v[202:205], v165 offset:6144
	ds_read_b128 v[206:209], v165 offset:7168
	global_load_lds_dwordx4 v154, s[20:21]
	s_add_i32 m0, s19, 0xe000
	s_nop 0
	global_load_lds_dwordx4 v156, s[20:21]
	s_waitcnt vmcnt(8)
	s_waitcnt lgkmcnt(0)
	s_barrier
	s_setprio 1
	s_waitcnt lgkmcnt(0)
	v_mfma_f32_16x16x32_bf16 v[140:143], v[48:51], v[178:181], v[140:143]
	v_mfma_f32_16x16x32_bf16 v[136:139], v[56:59], v[178:181], v[136:139]
	v_mfma_f32_16x16x32_bf16 v[124:127], v[48:51], v[186:189], v[124:127]
	v_mfma_f32_16x16x32_bf16 v[120:123], v[56:59], v[186:189], v[120:123]
	v_mfma_f32_16x16x32_bf16 v[108:111], v[48:51], v[194:197], v[108:111]
	v_mfma_f32_16x16x32_bf16 v[104:107], v[56:59], v[194:197], v[104:107]
	v_mfma_f32_16x16x32_bf16 v[92:95], v[48:51], v[202:205], v[92:95]
	v_mfma_f32_16x16x32_bf16 v[88:91], v[56:59], v[202:205], v[88:91]
	v_mfma_f32_16x16x32_bf16 v[140:143], v[52:55], v[182:185], v[140:143]
	v_mfma_f32_16x16x32_bf16 v[136:139], v[60:63], v[182:185], v[136:139]
	v_mfma_f32_16x16x32_bf16 v[124:127], v[52:55], v[190:193], v[124:127]
	v_mfma_f32_16x16x32_bf16 v[120:123], v[60:63], v[190:193], v[120:123]
	v_mfma_f32_16x16x32_bf16 v[108:111], v[52:55], v[198:201], v[108:111]
	v_mfma_f32_16x16x32_bf16 v[104:107], v[60:63], v[198:201], v[104:107]
	v_mfma_f32_16x16x32_bf16 v[92:95], v[52:55], v[206:209], v[92:95]
	v_mfma_f32_16x16x32_bf16 v[88:91], v[60:63], v[206:209], v[88:91]
	s_setprio 0
	s_setprio 1
	v_mfma_f32_16x16x32_bf16 v[132:135], v[158:161], v[178:181], v[132:135]
	v_mfma_f32_16x16x32_bf16 v[128:131], v[170:173], v[178:181], v[128:131]
	v_mfma_f32_16x16x32_bf16 v[116:119], v[158:161], v[186:189], v[116:119]
	v_mfma_f32_16x16x32_bf16 v[112:115], v[170:173], v[186:189], v[112:115]
	v_mfma_f32_16x16x32_bf16 v[100:103], v[158:161], v[194:197], v[100:103]
	v_mfma_f32_16x16x32_bf16 v[96:99], v[170:173], v[194:197], v[96:99]
	v_mfma_f32_16x16x32_bf16 v[84:87], v[158:161], v[202:205], v[84:87]
	v_mfma_f32_16x16x32_bf16 v[80:83], v[170:173], v[202:205], v[80:83]
	v_mfma_f32_16x16x32_bf16 v[132:135], v[166:169], v[182:185], v[132:135]
	v_mfma_f32_16x16x32_bf16 v[128:131], v[174:177], v[182:185], v[128:131]
	v_mfma_f32_16x16x32_bf16 v[116:119], v[166:169], v[190:193], v[116:119]
	v_mfma_f32_16x16x32_bf16 v[112:115], v[174:177], v[190:193], v[112:115]
	v_mfma_f32_16x16x32_bf16 v[100:103], v[166:169], v[198:201], v[100:103]
	v_mfma_f32_16x16x32_bf16 v[96:99], v[174:177], v[198:201], v[96:99]
	v_mfma_f32_16x16x32_bf16 v[84:87], v[166:169], v[206:209], v[84:87]
	v_mfma_f32_16x16x32_bf16 v[80:83], v[174:177], v[206:209], v[80:83]
	s_setprio 0
	s_barrier
	s_add_i32 s2, s33, s35
	s_mov_b32 m0, s2
	ds_read_b128 v[178:181], v165 offset:16384
	ds_read_b128 v[182:185], v165 offset:17408
	ds_read_b128 v[186:189], v165 offset:18432
	ds_read_b128 v[190:193], v165 offset:19456
	ds_read_b128 v[194:197], v165 offset:20480
	ds_read_b128 v[198:201], v165 offset:21504
	ds_read_b128 v[202:205], v165 offset:22528
	ds_read_b128 v[206:209], v165 offset:23552
	global_load_lds_dwordx4 v144, s[22:23]
	s_add_i32 m0, s2, 0x2000
	s_add_u32 s2, s22, 0x40000
	s_addc_u32 s3, s23, 0
	s_add_i32 s33, s34, s35
	global_load_lds_dwordx4 v148, s[22:23]
	s_mov_b32 m0, s33
	s_nop 0
	global_load_lds_dwordx4 v144, s[2:3]
	s_add_i32 m0, s33, 0x2000
	s_nop 0
	global_load_lds_dwordx4 v148, s[2:3]
	s_mov_b32 m0, s19
	s_nop 0
	global_load_lds_dwordx4 v152, s[24:25]
	s_mov_b32 m0, s36
	s_nop 0
	global_load_lds_dwordx4 v150, s[24:25]
	s_waitcnt vmcnt(8)
	s_waitcnt lgkmcnt(0)
	s_barrier
	s_setprio 1
	s_waitcnt lgkmcnt(0)
	v_mfma_f32_16x16x32_bf16 v[76:79], v[48:51], v[178:181], v[76:79]
	v_mfma_f32_16x16x32_bf16 v[72:75], v[56:59], v[178:181], v[72:75]
	v_mfma_f32_16x16x32_bf16 v[44:47], v[48:51], v[186:189], v[44:47]
	v_mfma_f32_16x16x32_bf16 v[40:43], v[56:59], v[186:189], v[40:43]
	v_mfma_f32_16x16x32_bf16 v[28:31], v[48:51], v[194:197], v[28:31]
	v_mfma_f32_16x16x32_bf16 v[24:27], v[56:59], v[194:197], v[24:27]
	v_mfma_f32_16x16x32_bf16 v[12:15], v[48:51], v[202:205], v[12:15]
	v_mfma_f32_16x16x32_bf16 v[8:11], v[56:59], v[202:205], v[8:11]
	v_mfma_f32_16x16x32_bf16 v[76:79], v[52:55], v[182:185], v[76:79]
	v_mfma_f32_16x16x32_bf16 v[72:75], v[60:63], v[182:185], v[72:75]
	v_mfma_f32_16x16x32_bf16 v[44:47], v[52:55], v[190:193], v[44:47]
	v_mfma_f32_16x16x32_bf16 v[40:43], v[60:63], v[190:193], v[40:43]
	v_mfma_f32_16x16x32_bf16 v[28:31], v[52:55], v[198:201], v[28:31]
	v_mfma_f32_16x16x32_bf16 v[24:27], v[60:63], v[198:201], v[24:27]
	v_mfma_f32_16x16x32_bf16 v[12:15], v[52:55], v[206:209], v[12:15]
	v_mfma_f32_16x16x32_bf16 v[8:11], v[60:63], v[206:209], v[8:11]
	s_setprio 0
	s_setprio 1
	v_mfma_f32_16x16x32_bf16 v[36:39], v[158:161], v[186:189], v[36:39]
	v_mfma_f32_16x16x32_bf16 v[32:35], v[170:173], v[186:189], v[32:35]
	v_mfma_f32_16x16x32_bf16 v[20:23], v[158:161], v[194:197], v[20:23]
	v_mfma_f32_16x16x32_bf16 v[16:19], v[170:173], v[194:197], v[16:19]
	v_mfma_f32_16x16x32_bf16 v[4:7], v[158:161], v[202:205], v[4:7]
	v_mfma_f32_16x16x32_bf16 v[0:3], v[170:173], v[202:205], v[0:3]
	v_mfma_f32_16x16x32_bf16 v[48:51], v[158:161], v[178:181], v[68:71]
	v_mfma_f32_16x16x32_bf16 v[52:55], v[170:173], v[178:181], v[64:67]
	v_mfma_f32_16x16x32_bf16 v[36:39], v[166:169], v[190:193], v[36:39]
	v_mfma_f32_16x16x32_bf16 v[32:35], v[174:177], v[190:193], v[32:35]
	v_mfma_f32_16x16x32_bf16 v[20:23], v[166:169], v[198:201], v[20:23]
	v_mfma_f32_16x16x32_bf16 v[16:19], v[174:177], v[198:201], v[16:19]
	v_mfma_f32_16x16x32_bf16 v[4:7], v[166:169], v[206:209], v[4:7]
	v_mfma_f32_16x16x32_bf16 v[0:3], v[174:177], v[206:209], v[0:3]
	v_mfma_f32_16x16x32_bf16 v[48:51], v[166:169], v[182:185], v[48:51]
	v_mfma_f32_16x16x32_bf16 v[52:55], v[174:177], v[182:185], v[52:55]
	s_setprio 0
	s_barrier
; #define PG8_STAGE(bufoff, gbase, voff) do { _Pragma("unroll") for (int _i = 0; _i < 2; ++_i) \
;         __builtin_amdgcn_global_load_lds((const unsigned*)((const char*)(gbase) + (voff)[_i]), (PG8_LAS unsigned*)(lds + (bufoff) + ldsw + _i * 8192), 16, 0, 0); } while (0)
; #define PG8_LDA(dst, b, h) do { _Pragma("unroll") for (int m = 0; m < 4; ++m) _Pragma("unroll") for (int k = 0; k < 2; ++k) dst[m][k] = *(const PG8_LAS bf16x8*)(lds + PG8_SA(b, h) + aoff + m * 2048 + k * 1024); } while (0)
; #define PG8_LDB(dst, b, h) do { _Pragma("unroll") for (int n = 0; n < 2; ++n) _Pragma("unroll") for (int k = 0; k < 2; ++k) dst[n][k] = *(const PG8_LAS bf16x8*)(lds + PG8_SB(b, h) + boff + n * 2048 + k * 1024); } while (0)
; #define PG8_MMA(ai, bj, At, Bt) do { __builtin_amdgcn_s_setprio(1); _Pragma("unroll") for (int m = 0; m < 4; ++m) _Pragma("unroll") for (int n = 0; n < 2; ++n) _Pragma("unroll") for (int k = 0; k < 2; ++k) \
;         acc[ai][bj][m][n] = __builtin_amdgcn_mfma_f32_16x16x32_bf16(Bt[n][k], At[m][k], acc[ai][bj][m][n], 0, 0, 0); __builtin_amdgcn_s_setprio(0); } while (0)
; #define PG8_WAIT_V(n) asm volatile("s_waitcnt vmcnt(" #n ")" ::: "memory")
; #define PG8_WAIT_L(n) asm volatile("s_waitcnt lgkmcnt(" #n ")" ::: "memory")
; #define PG8_BAR __builtin_amdgcn_s_barrier()
; template <class Epi, class Sched, bool ALIGN_EPI = false, bool SP2 = false>
; __device__ __forceinline__ void gemm_phase(PG8_LAS unsigned char* lds, const Gemm g, const Sched& S, const Epi& E, int tid_in) {
;     ...
;         for (int t = 0; t < nt; t += 2) {
;             const bool last = (t == nt - 2);
;             const char* a1 = cA + (size_t)(t + 1) * kstep;
;             const char* a2 = last ? nA : cA + (size_t)(t + 2) * kstep; const char* b2 = last ? nB : cB + (size_t)(t + 2) * kstep;
;             const char* a3 = a2 + kstep; const char* b3 = b2 + kstep;
;     ...
;             PG8_LDB(B0, 1, 0); PG8_LDB(B1, 1, 1); PG8_SCHED; PG8_LDA(At, 1, 0); PG8_STAGE(PG8_SA(0, 1), a2 + hstep, voffA);
;             PG8_WAIT_V(8); PG8_WAIT_L(0); PG8_BAR; PG8_MMA(0, 0, At, B0); PG8_MMA(0, 1, At, B1); PG8_BAR; PG8_SCHED;
;             PG8_LDA(At, 1, 1); PG8_STAGE(PG8_SB(1, 0), b3, voffB); PG8_STAGE(PG8_SB(1, 1), b3 + hstep, voffB); PG8_STAGE(PG8_SA(1, 0), a3, voffA);
;             PG8_WAIT_V(8); PG8_WAIT_L(0); PG8_BAR; PG8_MMA(1, 0, At, B0); PG8_MMA(1, 1, At, B1); PG8_BAR; PG8_SCHED;
	s_add_i32 s33, 0, 0x18000
	s_add_i32 s34, 0, 0x1c000
	v_add_u32_e32 v68, s33, v164
	v_add_u32_e32 v174, s34, v164
	ds_read_b128 v[56:59], v68
	ds_read_b128 v[60:63], v68 offset:1024
	ds_read_b128 v[64:67], v68 offset:2048
	ds_read_b128 v[68:71], v68 offset:3072
	ds_read_b128 v[158:161], v174
	ds_read_b128 v[166:169], v174 offset:1024
	ds_read_b128 v[170:173], v174 offset:2048
	ds_read_b128 v[174:177], v174 offset:3072
	s_add_u32 s2, s24, 0x40000
	s_addc_u32 s3, s25, 0
	s_mov_b32 m0, s37
	ds_read_b128 v[178:181], v165 offset:32768
	ds_read_b128 v[182:185], v165 offset:33792
	ds_read_b128 v[186:189], v165 offset:34816
	ds_read_b128 v[190:193], v165 offset:35840
	ds_read_b128 v[194:197], v165 offset:36864
	ds_read_b128 v[198:201], v165 offset:37888
	ds_read_b128 v[202:205], v165 offset:38912
	ds_read_b128 v[206:209], v165 offset:39936
	global_load_lds_dwordx4 v152, s[2:3]
	s_mov_b32 m0, s38
	s_nop 0
	global_load_lds_dwordx4 v150, s[2:3]
	s_waitcnt vmcnt(8)
	s_waitcnt lgkmcnt(0)
	s_barrier
	s_setprio 1
	s_waitcnt lgkmcnt(0)
	v_mfma_f32_16x16x32_bf16 v[140:143], v[56:59], v[178:181], v[140:143]
	v_mfma_f32_16x16x32_bf16 v[136:139], v[64:67], v[178:181], v[136:139]
	v_mfma_f32_16x16x32_bf16 v[124:127], v[56:59], v[186:189], v[124:127]
	v_mfma_f32_16x16x32_bf16 v[120:123], v[64:67], v[186:189], v[120:123]
	v_mfma_f32_16x16x32_bf16 v[108:111], v[56:59], v[194:197], v[108:111]
	v_mfma_f32_16x16x32_bf16 v[104:107], v[64:67], v[194:197], v[104:107]
	v_mfma_f32_16x16x32_bf16 v[92:95], v[56:59], v[202:205], v[92:95]
	v_mfma_f32_16x16x32_bf16 v[88:91], v[64:67], v[202:205], v[88:91]
	v_mfma_f32_16x16x32_bf16 v[140:143], v[60:63], v[182:185], v[140:143]
	v_mfma_f32_16x16x32_bf16 v[136:139], v[68:71], v[182:185], v[136:139]
	v_mfma_f32_16x16x32_bf16 v[124:127], v[60:63], v[190:193], v[124:127]
	v_mfma_f32_16x16x32_bf16 v[120:123], v[68:71], v[190:193], v[120:123]
	v_mfma_f32_16x16x32_bf16 v[108:111], v[60:63], v[198:201], v[108:111]
	v_mfma_f32_16x16x32_bf16 v[104:107], v[68:71], v[198:201], v[104:107]
	v_mfma_f32_16x16x32_bf16 v[92:95], v[60:63], v[206:209], v[92:95]
	v_mfma_f32_16x16x32_bf16 v[88:91], v[68:71], v[206:209], v[88:91]
	s_setprio 0
	s_setprio 1
	v_mfma_f32_16x16x32_bf16 v[132:135], v[158:161], v[178:181], v[132:135]
	v_mfma_f32_16x16x32_bf16 v[128:131], v[170:173], v[178:181], v[128:131]
	v_mfma_f32_16x16x32_bf16 v[116:119], v[158:161], v[186:189], v[116:119]
	v_mfma_f32_16x16x32_bf16 v[112:115], v[170:173], v[186:189], v[112:115]
	v_mfma_f32_16x16x32_bf16 v[100:103], v[158:161], v[194:197], v[100:103]
	v_mfma_f32_16x16x32_bf16 v[96:99], v[170:173], v[194:197], v[96:99]
	v_mfma_f32_16x16x32_bf16 v[84:87], v[158:161], v[202:205], v[84:87]
	v_mfma_f32_16x16x32_bf16 v[80:83], v[170:173], v[202:205], v[80:83]
	v_mfma_f32_16x16x32_bf16 v[132:135], v[166:169], v[182:185], v[132:135]
	v_mfma_f32_16x16x32_bf16 v[128:131], v[174:177], v[182:185], v[128:131]
	v_mfma_f32_16x16x32_bf16 v[116:119], v[166:169], v[190:193], v[116:119]
	v_mfma_f32_16x16x32_bf16 v[112:115], v[174:177], v[190:193], v[112:115]
	v_mfma_f32_16x16x32_bf16 v[100:103], v[166:169], v[198:201], v[100:103]
	v_mfma_f32_16x16x32_bf16 v[96:99], v[174:177], v[198:201], v[96:99]
	v_mfma_f32_16x16x32_bf16 v[84:87], v[166:169], v[206:209], v[84:87]
	v_mfma_f32_16x16x32_bf16 v[80:83], v[174:177], v[206:209], v[80:83]
	s_setprio 0
	s_barrier
	s_add_i32 s2, s33, s35
	s_add_u32 s98, s22, 0x80
	s_addc_u32 s99, s23, 0
	s_mov_b32 m0, s2
	ds_read_b128 v[178:181], v165 offset:49152
	ds_read_b128 v[182:185], v165 offset:50176
	ds_read_b128 v[186:189], v165 offset:51200
	ds_read_b128 v[190:193], v165 offset:52224
	ds_read_b128 v[194:197], v165 offset:53248
	ds_read_b128 v[198:201], v165 offset:54272
	ds_read_b128 v[202:205], v165 offset:55296
	ds_read_b128 v[206:209], v165 offset:56320
	global_load_lds_dwordx4 v144, s[98:99]
	s_add_i32 m0, s2, 0x2000
	s_add_u32 s2, s22, 0x40080
	s_addc_u32 s3, s23, 0
	s_add_i32 s22, s34, s35
	global_load_lds_dwordx4 v148, s[98:99]
	s_mov_b32 m0, s22
	s_nop 0
	global_load_lds_dwordx4 v144, s[2:3]
	s_add_i32 m0, s22, 0x2000
	s_nop 0
	global_load_lds_dwordx4 v148, s[2:3]
	s_add_u32 s98, s24, 0x80
	s_addc_u32 s99, s25, 0
	s_mov_b32 m0, s41
	s_nop 0
	global_load_lds_dwordx4 v152, s[98:99]
	s_mov_b32 m0, s42
	s_nop 0
	global_load_lds_dwordx4 v150, s[98:99]
	s_waitcnt vmcnt(8)
	s_waitcnt lgkmcnt(0)
	s_barrier
	s_setprio 1
	s_waitcnt lgkmcnt(0)
	v_mfma_f32_16x16x32_bf16 v[76:79], v[56:59], v[178:181], v[76:79]
	v_mfma_f32_16x16x32_bf16 v[72:75], v[64:67], v[178:181], v[72:75]
	v_mfma_f32_16x16x32_bf16 v[44:47], v[56:59], v[186:189], v[44:47]
	v_mfma_f32_16x16x32_bf16 v[40:43], v[64:67], v[186:189], v[40:43]
	v_mfma_f32_16x16x32_bf16 v[28:31], v[56:59], v[194:197], v[28:31]
	v_mfma_f32_16x16x32_bf16 v[24:27], v[64:67], v[194:197], v[24:27]
	v_mfma_f32_16x16x32_bf16 v[12:15], v[56:59], v[202:205], v[12:15]
	v_mfma_f32_16x16x32_bf16 v[8:11], v[64:67], v[202:205], v[8:11]
	v_mfma_f32_16x16x32_bf16 v[76:79], v[60:63], v[182:185], v[76:79]
	v_mfma_f32_16x16x32_bf16 v[72:75], v[68:71], v[182:185], v[72:75]
	v_mfma_f32_16x16x32_bf16 v[44:47], v[60:63], v[190:193], v[44:47]
	v_mfma_f32_16x16x32_bf16 v[40:43], v[68:71], v[190:193], v[40:43]
	v_mfma_f32_16x16x32_bf16 v[28:31], v[60:63], v[198:201], v[28:31]
	v_mfma_f32_16x16x32_bf16 v[24:27], v[68:71], v[198:201], v[24:27]
	v_mfma_f32_16x16x32_bf16 v[12:15], v[60:63], v[206:209], v[12:15]
	v_mfma_f32_16x16x32_bf16 v[8:11], v[68:71], v[206:209], v[8:11]
	s_setprio 0
	s_setprio 1
	v_mfma_f32_16x16x32_bf16 v[48:51], v[158:161], v[178:181], v[48:51]
	v_mfma_f32_16x16x32_bf16 v[68:71], v[166:169], v[182:185], v[48:51]
	v_mfma_f32_16x16x32_bf16 v[48:51], v[170:173], v[178:181], v[52:55]
	v_mfma_f32_16x16x32_bf16 v[36:39], v[158:161], v[186:189], v[36:39]
	v_mfma_f32_16x16x32_bf16 v[32:35], v[170:173], v[186:189], v[32:35]
	v_mfma_f32_16x16x32_bf16 v[20:23], v[158:161], v[194:197], v[20:23]
	v_mfma_f32_16x16x32_bf16 v[16:19], v[170:173], v[194:197], v[16:19]
	v_mfma_f32_16x16x32_bf16 v[4:7], v[158:161], v[202:205], v[4:7]
	v_mfma_f32_16x16x32_bf16 v[0:3], v[170:173], v[202:205], v[0:3]
	v_mfma_f32_16x16x32_bf16 v[64:67], v[174:177], v[182:185], v[48:51]
	v_mfma_f32_16x16x32_bf16 v[36:39], v[166:169], v[190:193], v[36:39]
	v_mfma_f32_16x16x32_bf16 v[32:35], v[174:177], v[190:193], v[32:35]
	v_mfma_f32_16x16x32_bf16 v[20:23], v[166:169], v[198:201], v[20:23]
	v_mfma_f32_16x16x32_bf16 v[16:19], v[174:177], v[198:201], v[16:19]
	v_mfma_f32_16x16x32_bf16 v[4:7], v[166:169], v[206:209], v[4:7]
	v_mfma_f32_16x16x32_bf16 v[0:3], v[174:177], v[206:209], v[0:3]
	s_setprio 0
	s_barrier
	s_add_i32 s49, s49, 2
	s_add_u32 s20, s20, 0x100
	s_addc_u32 s21, s21, 0
	s_add_u32 s47, s47, 0x100
	s_addc_u32 s48, s48, 0
	s_cmp_gt_u32 s49, 13
	s_cbranch_scc0 .LBB0_351
	s_and_b64 vcc, exec, s[6:7]
	s_cbranch_vccz .LBB0_354
	s_barrier

; __global__ void __launch_bounds__(NTHREADS, 2) mega_fwd(Params p_arg) {
	.amdhsa_kernel _Z8mega_fwd6Params
		.amdhsa_group_segment_fixed_size 0
		.amdhsa_private_segment_fixed_size 0
		.amdhsa_kernarg_size 456
		.amdhsa_user_sgpr_count 2
		.amdhsa_user_sgpr_dispatch_ptr 0
		.amdhsa_user_sgpr_queue_ptr 0
		.amdhsa_user_sgpr_kernarg_segment_ptr 1
		.amdhsa_user_sgpr_dispatch_id 0
		.amdhsa_user_sgpr_kernarg_preload_length 0
		.amdhsa_user_sgpr_kernarg_preload_offset 0
		.amdhsa_user_sgpr_private_segment_size 0
		.amdhsa_uses_dynamic_stack 0
		.amdhsa_enable_private_segment 0
		.amdhsa_system_sgpr_workgroup_id_x 1
		.amdhsa_system_sgpr_workgroup_id_y 0
		.amdhsa_system_sgpr_workgroup_id_z 0
		.amdhsa_system_sgpr_workgroup_info 0
		.amdhsa_system_vgpr_workitem_id 2
		.amdhsa_next_free_vgpr 256
		.amdhsa_next_free_sgpr 102
		.amdhsa_accum_offset 256
		.amdhsa_reserve_vcc 1
		.amdhsa_float_round_mode_32 0
		.amdhsa_float_round_mode_16_64 0
		.amdhsa_float_denorm_mode_32 3
		.amdhsa_float_denorm_mode_16_64 3
		.amdhsa_dx10_clamp 1
		.amdhsa_ieee_mode 1
		.amdhsa_fp16_overflow 0
		.amdhsa_tg_split 0
		.amdhsa_exception_fp_ieee_invalid_op 0
		.amdhsa_exception_fp_denorm_src 0
		.amdhsa_exception_fp_ieee_div_zero 0
		.amdhsa_exception_fp_ieee_overflow 0
		.amdhsa_exception_fp_ieee_underflow 0
		.amdhsa_exception_fp_ieee_inexact 0
		.amdhsa_exception_int_div_zero 0
	.end_amdhsa_kernel

; __global__ void __launch_bounds__(NTHREADS, 2) mega_fwd(Params p_arg) {
amdhsa.kernels:
  - .agpr_count:     0
    .args:
      - .offset:         0
        .size:           200
        .value_kind:     by_value
      - .offset:         200
        .size:           4
        .value_kind:     hidden_block_count_x
      - .offset:         204
        .size:           4
        .value_kind:     hidden_block_count_y
      - .offset:         208
        .size:           4
        .value_kind:     hidden_block_count_z
      - .offset:         212
        .size:           2
        .value_kind:     hidden_group_size_x
      - .offset:         214
        .size:           2
        .value_kind:     hidden_group_size_y
      - .offset:         216
        .size:           2
        .value_kind:     hidden_group_size_z
      - .offset:         218
        .size:           2
        .value_kind:     hidden_remainder_x
      - .offset:         220
        .size:           2
        .value_kind:     hidden_remainder_y
      - .offset:         222
        .size:           2
        .value_kind:     hidden_remainder_z
      - .offset:         240
        .size:           8
        .value_kind:     hidden_global_offset_x
      - .offset:         248
        .size:           8
        .value_kind:     hidden_global_offset_y
      - .offset:         256
        .size:           8
        .value_kind:     hidden_global_offset_z
      - .offset:         264
        .size:           2
        .value_kind:     hidden_grid_dims
      - .offset:         288
        .size:           8
        .value_kind:     hidden_multigrid_sync_arg
      - .offset:         320
        .size:           4
        .value_kind:     hidden_dynamic_lds_size
    .group_segment_fixed_size: 0
    .kernarg_segment_align: 8
    .kernarg_segment_size: 456
    .language:       OpenCL C
    .language_version:
      - 2
      - 0
    .max_flat_workgroup_size: 512
    .name:           _Z8mega_fwd6Params
    .private_segment_fixed_size: 0
    .sgpr_count:     108
    .sgpr_spill_count: 215
    .symbol:         _Z8mega_fwd6Params.kd
    .uniform_work_group_size: 1
    .uses_dynamic_stack: false
    .vgpr_count:     256
    .vgpr_spill_count: 0
    .wavefront_size: 64
